# deferred up/down conversion (layers 1,3) in compress-phase idle workgroups, non-temporal stores
# speedup vs baseline: 1.0042x; 1.0015x over previous
; #define LAS __attribute__((address_space(3)))
; __device__ __forceinline__ void tr_load(float (&v)[32], const float* W, int K, int N, int item, int lane) {
;     const int nblk = (N + 31) / 32, kb = item / nblk, nb = item - kb * nblk, k0 = 64 * kb, n0 = 32 * nb;
;     const int nn = n0 + (lane & 31); const bool ok = nn < N;
;     const float* p = W + (size_t)(k0 + (lane >> 5)) * N + (ok ? nn : 0);
; #pragma unroll
;     for (int i = 0; i < 32; ++i) { const float x = __builtin_nontemporal_load(p + (size_t)(2 * i) * N); v[i] = ok ? x : 0.f; }
; }
; __device__ __forceinline__ void tr_put(const float (&v)[32], LAS float* scr, int lane) {
; #pragma unroll
;     for (int i = 0; i < 32; ++i) scr[(2 * i + (lane >> 5)) * 33 + (lane & 31)] = v[i];
.Ldcv_nogain:
	v_add_u32_e32 v38, s42, v35
	v_mul_lo_u32 v38, v38, s37
	v_add_u32_e32 v39, s43, v34
	v_lshl_add_u32 v38, v39, 2, v38
	global_load_dword v98, v38, s[20:21] nt
	v_add_u32_e32 v38, s44, v38
	global_load_dword v99, v38, s[20:21] nt
	v_add_u32_e32 v38, s44, v38
	global_load_dword v100, v38, s[20:21] nt
	v_add_u32_e32 v38, s44, v38
	global_load_dword v101, v38, s[20:21] nt
	v_add_u32_e32 v38, s44, v38
	global_load_dword v102, v38, s[20:21] nt
	v_add_u32_e32 v38, s44, v38
	global_load_dword v103, v38, s[20:21] nt
	v_add_u32_e32 v38, s44, v38
	global_load_dword v104, v38, s[20:21] nt
	v_add_u32_e32 v38, s44, v38
	global_load_dword v105, v38, s[20:21] nt
	v_add_u32_e32 v38, s44, v38
	global_load_dword v106, v38, s[20:21] nt
	v_add_u32_e32 v38, s44, v38
	global_load_dword v107, v38, s[20:21] nt
	v_add_u32_e32 v38, s44, v38
	global_load_dword v108, v38, s[20:21] nt
	v_add_u32_e32 v38, s44, v38
	global_load_dword v109, v38, s[20:21] nt
	v_add_u32_e32 v38, s44, v38
	global_load_dword v110, v38, s[20:21] nt
	v_add_u32_e32 v38, s44, v38
	global_load_dword v111, v38, s[20:21] nt
	v_add_u32_e32 v38, s44, v38
	global_load_dword v112, v38, s[20:21] nt
	v_add_u32_e32 v38, s44, v38
	global_load_dword v113, v38, s[20:21] nt
	v_add_u32_e32 v38, s44, v38
	global_load_dword v114, v38, s[20:21] nt
	v_add_u32_e32 v38, s44, v38
	global_load_dword v115, v38, s[20:21] nt
	v_add_u32_e32 v38, s44, v38
	global_load_dword v116, v38, s[20:21] nt
	v_add_u32_e32 v38, s44, v38
	global_load_dword v117, v38, s[20:21] nt
	v_add_u32_e32 v38, s44, v38
	global_load_dword v118, v38, s[20:21] nt
	v_add_u32_e32 v38, s44, v38
	global_load_dword v119, v38, s[20:21] nt
	v_add_u32_e32 v38, s44, v38
	global_load_dword v120, v38, s[20:21] nt
	v_add_u32_e32 v38, s44, v38
	global_load_dword v121, v38, s[20:21] nt
	v_add_u32_e32 v38, s44, v38
	global_load_dword v204, v38, s[20:21] nt
	v_add_u32_e32 v38, s44, v38
	global_load_dword v205, v38, s[20:21] nt
	v_add_u32_e32 v38, s44, v38
	global_load_dword v206, v38, s[20:21] nt
	v_add_u32_e32 v38, s44, v38
	global_load_dword v207, v38, s[20:21] nt
	v_add_u32_e32 v38, s44, v38
	global_load_dword v208, v38, s[20:21] nt
	v_add_u32_e32 v38, s44, v38
	global_load_dword v209, v38, s[20:21] nt
	v_add_u32_e32 v38, s44, v38
	global_load_dword v210, v38, s[20:21] nt
	v_add_u32_e32 v38, s44, v38
	global_load_dword v211, v38, s[20:21] nt
	v_add_u32_e32 v40, s43, v43
	v_mul_lo_u32 v40, v40, s38
	v_lshl_add_u32 v41, v42, 3, s42
	v_lshl_add_u32 v40, v41, 1, v40
	s_waitcnt vmcnt(31)
	ds_write_b32 v36, v98
	s_waitcnt vmcnt(30)
	ds_write_b32 v36, v99 offset:264
	s_waitcnt vmcnt(29)
	ds_write_b32 v36, v100 offset:528
	s_waitcnt vmcnt(28)
	ds_write_b32 v36, v101 offset:792
	s_waitcnt vmcnt(27)
	ds_write_b32 v36, v102 offset:1056
	s_waitcnt vmcnt(26)
	ds_write_b32 v36, v103 offset:1320
	s_waitcnt vmcnt(25)
	ds_write_b32 v36, v104 offset:1584
	s_waitcnt vmcnt(24)
	ds_write_b32 v36, v105 offset:1848
	s_waitcnt vmcnt(23)
	ds_write_b32 v36, v106 offset:2112
	s_waitcnt vmcnt(22)
	ds_write_b32 v36, v107 offset:2376
	s_waitcnt vmcnt(21)
	ds_write_b32 v36, v108 offset:2640
	s_waitcnt vmcnt(20)
	ds_write_b32 v36, v109 offset:2904
	s_waitcnt vmcnt(19)
	ds_write_b32 v36, v110 offset:3168
	s_waitcnt vmcnt(18)
	ds_write_b32 v36, v111 offset:3432
	s_waitcnt vmcnt(17)
	ds_write_b32 v36, v112 offset:3696
	s_waitcnt vmcnt(16)
	ds_write_b32 v36, v113 offset:3960
	s_waitcnt vmcnt(15)
	ds_write_b32 v36, v114 offset:4224
	s_waitcnt vmcnt(14)
	ds_write_b32 v36, v115 offset:4488
	s_waitcnt vmcnt(13)
	ds_write_b32 v36, v116 offset:4752
	s_waitcnt vmcnt(12)
	ds_write_b32 v36, v117 offset:5016
	s_waitcnt vmcnt(11)
; #define LAS __attribute__((address_space(3)))
; __device__ __forceinline__ void tr_put(const float (&v)[32], LAS float* scr, int lane) {
; #pragma unroll
;     for (int i = 0; i < 32; ++i) scr[(2 * i + (lane >> 5)) * 33 + (lane & 31)] = v[i];
; }
; __device__ __forceinline__ void tr_put_gain(const float (&v)[32], LAS float* scr, int lane, const LAS float* gk) {
; #pragma unroll
;     for (int i = 0; i < 32; ++i) scr[(2 * i + (lane >> 5)) * 33 + (lane & 31)] = v[i] * gk[2 * i + (lane >> 5)];
; }
; __device__ __forceinline__ void tr_store(bf16_t* WT, int K, int N, LAS float* scr, int item, int lane) {
;     const int nblk = (N + 31) / 32, kb = item / nblk, nb = item - kb * nblk, k0 = 64 * kb, n0 = 32 * nb;
;     const int c = lane & 7;
; #pragma unroll
;     for (int j = 0; j < 4; ++j) { const int n = (lane >> 3) + 8 * j; const LAS float* s = scr + (8 * c) * 33 + n;
;         v4u o; o.x = pkbf(s[0 * 33], s[1 * 33]); o.y = pkbf(s[2 * 33], s[3 * 33]); o.z = pkbf(s[4 * 33], s[5 * 33]); o.w = pkbf(s[6 * 33], s[7 * 33]);
;         *(v4u*)(WT + (size_t)(n0 + n) * K + k0 + 8 * c) = o; }
	ds_write_b32 v36, v118 offset:5280
	s_waitcnt vmcnt(10)
	ds_write_b32 v36, v119 offset:5544
	s_waitcnt vmcnt(9)
	ds_write_b32 v36, v120 offset:5808
	s_waitcnt vmcnt(8)
	ds_write_b32 v36, v121 offset:6072
	s_waitcnt vmcnt(7)
	ds_write_b32 v36, v204 offset:6336
	s_waitcnt vmcnt(6)
	ds_write_b32 v36, v205 offset:6600
	s_waitcnt vmcnt(5)
	ds_write_b32 v36, v206 offset:6864
	s_waitcnt vmcnt(4)
	ds_write_b32 v36, v207 offset:7128
	s_waitcnt vmcnt(3)
	ds_write_b32 v36, v208 offset:7392
	s_waitcnt vmcnt(2)
	ds_write_b32 v36, v209 offset:7656
	s_waitcnt vmcnt(1)
	ds_write_b32 v36, v210 offset:7920
	s_waitcnt vmcnt(0)
	ds_write_b32 v36, v211 offset:8184
	s_waitcnt lgkmcnt(0)
	ds_read2_b32 v[98:99], v37 offset0:0 offset1:33
	ds_read2_b32 v[100:101], v37 offset0:66 offset1:99
	ds_read2_b32 v[102:103], v37 offset0:132 offset1:165
	ds_read2_b32 v[104:105], v37 offset0:198 offset1:231
	ds_read2_b32 v[106:107], v37 offset0:8 offset1:41
	ds_read2_b32 v[108:109], v37 offset0:74 offset1:107
	ds_read2_b32 v[110:111], v37 offset0:140 offset1:173
	ds_read2_b32 v[112:113], v37 offset0:206 offset1:239
	ds_read2_b32 v[114:115], v37 offset0:16 offset1:49
	ds_read2_b32 v[116:117], v37 offset0:82 offset1:115
	ds_read2_b32 v[118:119], v37 offset0:148 offset1:181
	ds_read2_b32 v[120:121], v37 offset0:214 offset1:247
	ds_read2_b32 v[204:205], v37 offset0:24 offset1:57
	ds_read2_b32 v[206:207], v37 offset0:90 offset1:123
	ds_read2_b32 v[208:209], v37 offset0:156 offset1:189
	ds_read2_b32 v[210:211], v37 offset0:222 offset1:255
	s_waitcnt lgkmcnt(12)
	v_mul_f32_e32 v98, v98, v222
	v_mul_f32_e32 v99, v99, v223
	v_mul_f32_e32 v100, v100, v224
	v_mul_f32_e32 v101, v101, v225
	v_mul_f32_e32 v102, v102, v226
	v_mul_f32_e32 v103, v103, v227
	v_mul_f32_e32 v104, v104, v228
	v_mul_f32_e32 v105, v105, v229
	v_cvt_pk_bf16_f32 v244, v98, v99
	v_cvt_pk_bf16_f32 v245, v100, v101
	v_cvt_pk_bf16_f32 v246, v102, v103
	v_cvt_pk_bf16_f32 v247, v104, v105
	global_store_dwordx4 v40, v[244:247], s[22:23] nt
	v_add_u32_e32 v40, s45, v40
	s_waitcnt lgkmcnt(8)
	v_mul_f32_e32 v106, v106, v222
	v_mul_f32_e32 v107, v107, v223
	v_mul_f32_e32 v108, v108, v224
	v_mul_f32_e32 v109, v109, v225
	v_mul_f32_e32 v110, v110, v226
	v_mul_f32_e32 v111, v111, v227
	v_mul_f32_e32 v112, v112, v228
	v_mul_f32_e32 v113, v113, v229
	v_cvt_pk_bf16_f32 v230, v106, v107
	v_cvt_pk_bf16_f32 v231, v108, v109
	v_cvt_pk_bf16_f32 v232, v110, v111
	v_cvt_pk_bf16_f32 v233, v112, v113
	global_store_dwordx4 v40, v[230:233], s[22:23] nt
	v_add_u32_e32 v40, s45, v40
	s_waitcnt lgkmcnt(4)
	v_mul_f32_e32 v114, v114, v222
	v_mul_f32_e32 v115, v115, v223
	v_mul_f32_e32 v116, v116, v224
	v_mul_f32_e32 v117, v117, v225
	v_mul_f32_e32 v118, v118, v226
	v_mul_f32_e32 v119, v119, v227
	v_mul_f32_e32 v120, v120, v228
	v_mul_f32_e32 v121, v121, v229
	v_cvt_pk_bf16_f32 v244, v114, v115
	v_cvt_pk_bf16_f32 v245, v116, v117
	v_cvt_pk_bf16_f32 v246, v118, v119
	v_cvt_pk_bf16_f32 v247, v120, v121
	global_store_dwordx4 v40, v[244:247], s[22:23] nt
	v_add_u32_e32 v40, s45, v40
	s_waitcnt lgkmcnt(0)
	v_mul_f32_e32 v204, v204, v222
	v_mul_f32_e32 v205, v205, v223
	v_mul_f32_e32 v206, v206, v224
	v_mul_f32_e32 v207, v207, v225
	v_mul_f32_e32 v208, v208, v226
	v_mul_f32_e32 v209, v209, v227
	v_mul_f32_e32 v210, v210, v228
	v_mul_f32_e32 v211, v211, v229
	v_cvt_pk_bf16_f32 v230, v204, v205
	v_cvt_pk_bf16_f32 v231, v206, v207
	v_cvt_pk_bf16_f32 v232, v208, v209
	v_cvt_pk_bf16_f32 v233, v210, v211
	global_store_dwordx4 v40, v[230:233], s[22:23] nt
	s_add_i32 s30, s30, 0x400
	s_cmp_lt_u32 s30, 0x2000
	s_cbranch_scc1 .Ldcv_item
	s_add_i32 s17, s17, 1
	s_cmp_lt_u32 s17, 2
	s_cbranch_scc1 .Ldcv_matrix
	s_waitcnt vmcnt(0) lgkmcnt(0)
